# hand-rewritten top-256 selection in indexer: branch-free sortable conversion, rotating-SGPR ballot counting, writelane mask build
# baseline (speedup 1.0000x reference)
.LBB0_123:
	s_lshr_b32 s27, s10, 9
	s_add_i32 s27, s27, 1
	s_add_i32 s28, s10, 1
	s_add_i32 s30, s10, 2
	s_brev_b32 s29, 1
	ds_read2st64_b32 v[66:67], v250 offset0:0 offset1:1
	ds_read2st64_b32 v[68:69], v250 offset0:2 offset1:3
	ds_read2st64_b32 v[70:71], v250 offset0:4 offset1:5
	ds_read2st64_b32 v[72:73], v250 offset0:6 offset1:7
	ds_read2st64_b32 v[98:99], v250 offset0:32 offset1:33
	ds_read2st64_b32 v[100:101], v250 offset0:34 offset1:35
	ds_read2st64_b32 v[102:103], v250 offset0:36 offset1:37
	ds_read2st64_b32 v[104:105], v250 offset0:38 offset1:39
	ds_read2st64_b32 v[74:75], v250 offset0:8 offset1:9
	ds_read2st64_b32 v[76:77], v250 offset0:10 offset1:11
	ds_read2st64_b32 v[78:79], v250 offset0:12 offset1:13
	ds_read2st64_b32 v[80:81], v250 offset0:14 offset1:15
	s_waitcnt lgkmcnt(8)
	v_cmp_gt_i32_e64 s[34:35], s28, v178
	v_ashrrev_i32_e32 v130, 31, v66
	v_or_b32_e32 v130, s29, v130
	v_xor_b32_e32 v66, v66, v130
	v_cndmask_b32_e64 v66, 0, v66, s[34:35]
	s_sub_i32 s1, s28, 64
	v_cmp_gt_i32_e64 s[36:37], s1, v178
	v_ashrrev_i32_e32 v131, 31, v67
	v_or_b32_e32 v131, s29, v131
	v_xor_b32_e32 v67, v67, v131
	v_cndmask_b32_e64 v67, 0, v67, s[36:37]
	s_sub_i32 s0, s28, 128
	v_cmp_gt_i32_e64 s[38:39], s0, v178
	v_ashrrev_i32_e32 v130, 31, v68
	v_or_b32_e32 v130, s29, v130
	v_xor_b32_e32 v68, v68, v130
	v_cndmask_b32_e64 v68, 0, v68, s[38:39]
	s_sub_i32 s1, s28, 192
	v_cmp_gt_i32_e64 s[40:41], s1, v178
	v_ashrrev_i32_e32 v131, 31, v69
	v_or_b32_e32 v131, s29, v131
	v_xor_b32_e32 v69, v69, v131
	v_cndmask_b32_e64 v69, 0, v69, s[40:41]
	s_sub_i32 s0, s28, 256
	v_cmp_gt_i32_e64 s[34:35], s0, v178
	v_ashrrev_i32_e32 v130, 31, v70
	v_or_b32_e32 v130, s29, v130
	v_xor_b32_e32 v70, v70, v130
	v_cndmask_b32_e64 v70, 0, v70, s[34:35]
	s_sub_i32 s1, s28, 320
	v_cmp_gt_i32_e64 s[36:37], s1, v178
	v_ashrrev_i32_e32 v131, 31, v71
	v_or_b32_e32 v131, s29, v131
	v_xor_b32_e32 v71, v71, v131
	v_cndmask_b32_e64 v71, 0, v71, s[36:37]
	s_sub_i32 s0, s28, 384
	v_cmp_gt_i32_e64 s[38:39], s0, v178
	v_ashrrev_i32_e32 v130, 31, v72
	v_or_b32_e32 v130, s29, v130
	v_xor_b32_e32 v72, v72, v130
	v_cndmask_b32_e64 v72, 0, v72, s[38:39]
	s_sub_i32 s1, s28, 448
	v_cmp_gt_i32_e64 s[40:41], s1, v178
	v_ashrrev_i32_e32 v131, 31, v73
	v_or_b32_e32 v131, s29, v131
	v_xor_b32_e32 v73, v73, v131
	v_cndmask_b32_e64 v73, 0, v73, s[40:41]
	ds_read2st64_b32 v[106:107], v250 offset0:40 offset1:41
	ds_read2st64_b32 v[108:109], v250 offset0:42 offset1:43
	ds_read2st64_b32 v[110:111], v250 offset0:44 offset1:45
	ds_read2st64_b32 v[112:113], v250 offset0:46 offset1:47
	s_waitcnt lgkmcnt(8)
	v_cmp_gt_i32_e64 s[34:35], s30, v178
	v_ashrrev_i32_e32 v130, 31, v98
	v_or_b32_e32 v130, s29, v130
	v_xor_b32_e32 v98, v98, v130
	v_cndmask_b32_e64 v98, 0, v98, s[34:35]
	s_sub_i32 s1, s30, 64
	v_cmp_gt_i32_e64 s[36:37], s1, v178
	v_ashrrev_i32_e32 v131, 31, v99
	v_or_b32_e32 v131, s29, v131
	v_xor_b32_e32 v99, v99, v131
	v_cndmask_b32_e64 v99, 0, v99, s[36:37]
	s_sub_i32 s0, s30, 128
	v_cmp_gt_i32_e64 s[38:39], s0, v178
	v_ashrrev_i32_e32 v130, 31, v100
	v_or_b32_e32 v130, s29, v130
	v_xor_b32_e32 v100, v100, v130
	v_cndmask_b32_e64 v100, 0, v100, s[38:39]
	s_sub_i32 s1, s30, 192
	v_cmp_gt_i32_e64 s[40:41], s1, v178
	v_ashrrev_i32_e32 v131, 31, v101
	v_or_b32_e32 v131, s29, v131
	v_xor_b32_e32 v101, v101, v131
	v_cndmask_b32_e64 v101, 0, v101, s[40:41]
	s_sub_i32 s0, s30, 256
	v_cmp_gt_i32_e64 s[34:35], s0, v178
	v_ashrrev_i32_e32 v130, 31, v102
	v_or_b32_e32 v130, s29, v130
	v_xor_b32_e32 v102, v102, v130
	v_cndmask_b32_e64 v102, 0, v102, s[34:35]
	s_sub_i32 s1, s30, 320
	v_cmp_gt_i32_e64 s[36:37], s1, v178
	v_ashrrev_i32_e32 v131, 31, v103
	v_or_b32_e32 v131, s29, v131
	v_xor_b32_e32 v103, v103, v131
	v_cndmask_b32_e64 v103, 0, v103, s[36:37]
	s_sub_i32 s0, s30, 384
	v_cmp_gt_i32_e64 s[38:39], s0, v178
	v_ashrrev_i32_e32 v130, 31, v104
	v_or_b32_e32 v130, s29, v130
	v_xor_b32_e32 v104, v104, v130
	v_cndmask_b32_e64 v104, 0, v104, s[38:39]
	s_sub_i32 s1, s30, 448
	v_cmp_gt_i32_e64 s[40:41], s1, v178
	v_ashrrev_i32_e32 v131, 31, v105
	v_or_b32_e32 v131, s29, v131
	v_xor_b32_e32 v105, v105, v131
	v_cndmask_b32_e64 v105, 0, v105, s[40:41]
	s_cmp_lt_u32 s27, 2
	s_cbranch_scc1 .Lsel_cdone
	ds_read2st64_b32 v[82:83], v250 offset0:16 offset1:17
	ds_read2st64_b32 v[84:85], v250 offset0:18 offset1:19
	ds_read2st64_b32 v[86:87], v250 offset0:20 offset1:21
	ds_read2st64_b32 v[88:89], v250 offset0:22 offset1:23
	s_waitcnt lgkmcnt(8)
	s_sub_i32 s0, s28, 512
	v_cmp_gt_i32_e64 s[34:35], s0, v178
	v_ashrrev_i32_e32 v130, 31, v74
	v_or_b32_e32 v130, s29, v130
	v_xor_b32_e32 v74, v74, v130
	v_cndmask_b32_e64 v74, 0, v74, s[34:35]
	s_sub_i32 s1, s28, 576
	v_cmp_gt_i32_e64 s[36:37], s1, v178
	v_ashrrev_i32_e32 v131, 31, v75
	v_or_b32_e32 v131, s29, v131
	v_xor_b32_e32 v75, v75, v131
	v_cndmask_b32_e64 v75, 0, v75, s[36:37]
	s_sub_i32 s0, s28, 640
	v_cmp_gt_i32_e64 s[38:39], s0, v178
	v_ashrrev_i32_e32 v130, 31, v76
	v_or_b32_e32 v130, s29, v130
	v_xor_b32_e32 v76, v76, v130
	v_cndmask_b32_e64 v76, 0, v76, s[38:39]
	s_sub_i32 s1, s28, 704
	v_cmp_gt_i32_e64 s[40:41], s1, v178
	v_ashrrev_i32_e32 v131, 31, v77
	v_or_b32_e32 v131, s29, v131
	v_xor_b32_e32 v77, v77, v131
	v_cndmask_b32_e64 v77, 0, v77, s[40:41]
	s_sub_i32 s0, s28, 768
	v_cmp_gt_i32_e64 s[34:35], s0, v178
	v_ashrrev_i32_e32 v130, 31, v78
	v_or_b32_e32 v130, s29, v130
	v_xor_b32_e32 v78, v78, v130
	v_cndmask_b32_e64 v78, 0, v78, s[34:35]
	s_sub_i32 s1, s28, 832
	v_cmp_gt_i32_e64 s[36:37], s1, v178
	v_ashrrev_i32_e32 v131, 31, v79
	v_or_b32_e32 v131, s29, v131
	v_xor_b32_e32 v79, v79, v131
	v_cndmask_b32_e64 v79, 0, v79, s[36:37]
	s_sub_i32 s0, s28, 896
	v_cmp_gt_i32_e64 s[38:39], s0, v178
	v_ashrrev_i32_e32 v130, 31, v80
	v_or_b32_e32 v130, s29, v130
	v_xor_b32_e32 v80, v80, v130
	v_cndmask_b32_e64 v80, 0, v80, s[38:39]
	s_sub_i32 s1, s28, 960
	v_cmp_gt_i32_e64 s[40:41], s1, v178
	v_ashrrev_i32_e32 v131, 31, v81
	v_or_b32_e32 v131, s29, v131
	v_xor_b32_e32 v81, v81, v131
	v_cndmask_b32_e64 v81, 0, v81, s[40:41]
	ds_read2st64_b32 v[114:115], v250 offset0:48 offset1:49
	ds_read2st64_b32 v[116:117], v250 offset0:50 offset1:51
	ds_read2st64_b32 v[118:119], v250 offset0:52 offset1:53
	ds_read2st64_b32 v[120:121], v250 offset0:54 offset1:55
	s_waitcnt lgkmcnt(8)
	s_sub_i32 s0, s30, 512
	v_cmp_gt_i32_e64 s[34:35], s0, v178
	v_ashrrev_i32_e32 v130, 31, v106
	v_or_b32_e32 v130, s29, v130
	v_xor_b32_e32 v106, v106, v130
	v_cndmask_b32_e64 v106, 0, v106, s[34:35]
	s_sub_i32 s1, s30, 576
	v_cmp_gt_i32_e64 s[36:37], s1, v178
	v_ashrrev_i32_e32 v131, 31, v107
	v_or_b32_e32 v131, s29, v131
	v_xor_b32_e32 v107, v107, v131
	v_cndmask_b32_e64 v107, 0, v107, s[36:37]
	s_sub_i32 s0, s30, 640
	v_cmp_gt_i32_e64 s[38:39], s0, v178
	v_ashrrev_i32_e32 v130, 31, v108
	v_or_b32_e32 v130, s29, v130
	v_xor_b32_e32 v108, v108, v130
	v_cndmask_b32_e64 v108, 0, v108, s[38:39]
	s_sub_i32 s1, s30, 704
	v_cmp_gt_i32_e64 s[40:41], s1, v178
	v_ashrrev_i32_e32 v131, 31, v109
	v_or_b32_e32 v131, s29, v131
	v_xor_b32_e32 v109, v109, v131
	v_cndmask_b32_e64 v109, 0, v109, s[40:41]
	s_sub_i32 s0, s30, 768
	v_cmp_gt_i32_e64 s[34:35], s0, v178
	v_ashrrev_i32_e32 v130, 31, v110
	v_or_b32_e32 v130, s29, v130
	v_xor_b32_e32 v110, v110, v130
	v_cndmask_b32_e64 v110, 0, v110, s[34:35]
	s_sub_i32 s1, s30, 832
	v_cmp_gt_i32_e64 s[36:37], s1, v178
	v_ashrrev_i32_e32 v131, 31, v111
	v_or_b32_e32 v131, s29, v131
	v_xor_b32_e32 v111, v111, v131
	v_cndmask_b32_e64 v111, 0, v111, s[36:37]
	s_sub_i32 s0, s30, 896
	v_cmp_gt_i32_e64 s[38:39], s0, v178
	v_ashrrev_i32_e32 v130, 31, v112
	v_or_b32_e32 v130, s29, v130
	v_xor_b32_e32 v112, v112, v130
	v_cndmask_b32_e64 v112, 0, v112, s[38:39]
	s_sub_i32 s1, s30, 960
	v_cmp_gt_i32_e64 s[40:41], s1, v178
	v_ashrrev_i32_e32 v131, 31, v113
	v_or_b32_e32 v131, s29, v131
	v_xor_b32_e32 v113, v113, v131
	v_cndmask_b32_e64 v113, 0, v113, s[40:41]
	s_cmp_lt_u32 s27, 3
	s_cbranch_scc1 .Lsel_cdone
	ds_read2st64_b32 v[90:91], v250 offset0:24 offset1:25
	ds_read2st64_b32 v[92:93], v250 offset0:26 offset1:27
	ds_read2st64_b32 v[94:95], v250 offset0:28 offset1:29
	ds_read2st64_b32 v[96:97], v250 offset0:30 offset1:31
	s_waitcnt lgkmcnt(8)
	s_sub_i32 s0, s28, 1024
	v_cmp_gt_i32_e64 s[34:35], s0, v178
	v_ashrrev_i32_e32 v130, 31, v82
	v_or_b32_e32 v130, s29, v130
	v_xor_b32_e32 v82, v82, v130
	v_cndmask_b32_e64 v82, 0, v82, s[34:35]
	s_sub_i32 s1, s28, 1088
	v_cmp_gt_i32_e64 s[36:37], s1, v178
	v_ashrrev_i32_e32 v131, 31, v83
	v_or_b32_e32 v131, s29, v131
	v_xor_b32_e32 v83, v83, v131
	v_cndmask_b32_e64 v83, 0, v83, s[36:37]
	s_sub_i32 s0, s28, 1152
	v_cmp_gt_i32_e64 s[38:39], s0, v178
	v_ashrrev_i32_e32 v130, 31, v84
	v_or_b32_e32 v130, s29, v130
	v_xor_b32_e32 v84, v84, v130
	v_cndmask_b32_e64 v84, 0, v84, s[38:39]
	s_sub_i32 s1, s28, 1216
	v_cmp_gt_i32_e64 s[40:41], s1, v178
	v_ashrrev_i32_e32 v131, 31, v85
	v_or_b32_e32 v131, s29, v131
	v_xor_b32_e32 v85, v85, v131
	v_cndmask_b32_e64 v85, 0, v85, s[40:41]
	s_sub_i32 s0, s28, 1280
	v_cmp_gt_i32_e64 s[34:35], s0, v178
	v_ashrrev_i32_e32 v130, 31, v86
	v_or_b32_e32 v130, s29, v130
	v_xor_b32_e32 v86, v86, v130
	v_cndmask_b32_e64 v86, 0, v86, s[34:35]
	s_sub_i32 s1, s28, 1344
	v_cmp_gt_i32_e64 s[36:37], s1, v178
	v_ashrrev_i32_e32 v131, 31, v87
	v_or_b32_e32 v131, s29, v131
	v_xor_b32_e32 v87, v87, v131
	v_cndmask_b32_e64 v87, 0, v87, s[36:37]
	s_sub_i32 s0, s28, 1408
	v_cmp_gt_i32_e64 s[38:39], s0, v178
	v_ashrrev_i32_e32 v130, 31, v88
	v_or_b32_e32 v130, s29, v130
	v_xor_b32_e32 v88, v88, v130
	v_cndmask_b32_e64 v88, 0, v88, s[38:39]
	s_sub_i32 s1, s28, 1472
	v_cmp_gt_i32_e64 s[40:41], s1, v178
	v_ashrrev_i32_e32 v131, 31, v89
	v_or_b32_e32 v131, s29, v131
	v_xor_b32_e32 v89, v89, v131
	v_cndmask_b32_e64 v89, 0, v89, s[40:41]
	ds_read2st64_b32 v[122:123], v250 offset0:56 offset1:57
	ds_read2st64_b32 v[124:125], v250 offset0:58 offset1:59
	ds_read2st64_b32 v[126:127], v250 offset0:60 offset1:61
	ds_read2st64_b32 v[128:129], v250 offset0:62 offset1:63
	s_waitcnt lgkmcnt(8)
	s_sub_i32 s0, s30, 1024
	v_cmp_gt_i32_e64 s[34:35], s0, v178
	v_ashrrev_i32_e32 v130, 31, v114
	v_or_b32_e32 v130, s29, v130
	v_xor_b32_e32 v114, v114, v130
	v_cndmask_b32_e64 v114, 0, v114, s[34:35]
	s_sub_i32 s1, s30, 1088
	v_cmp_gt_i32_e64 s[36:37], s1, v178
	v_ashrrev_i32_e32 v131, 31, v115
	v_or_b32_e32 v131, s29, v131
	v_xor_b32_e32 v115, v115, v131
	v_cndmask_b32_e64 v115, 0, v115, s[36:37]
	s_sub_i32 s0, s30, 1152
	v_cmp_gt_i32_e64 s[38:39], s0, v178
	v_ashrrev_i32_e32 v130, 31, v116
	v_or_b32_e32 v130, s29, v130
	v_xor_b32_e32 v116, v116, v130
	v_cndmask_b32_e64 v116, 0, v116, s[38:39]
	s_sub_i32 s1, s30, 1216
	v_cmp_gt_i32_e64 s[40:41], s1, v178
	v_ashrrev_i32_e32 v131, 31, v117
	v_or_b32_e32 v131, s29, v131
	v_xor_b32_e32 v117, v117, v131
	v_cndmask_b32_e64 v117, 0, v117, s[40:41]
	s_sub_i32 s0, s30, 1280
	v_cmp_gt_i32_e64 s[34:35], s0, v178
	v_ashrrev_i32_e32 v130, 31, v118
	v_or_b32_e32 v130, s29, v130
	v_xor_b32_e32 v118, v118, v130
	v_cndmask_b32_e64 v118, 0, v118, s[34:35]
	s_sub_i32 s1, s30, 1344
	v_cmp_gt_i32_e64 s[36:37], s1, v178
	v_ashrrev_i32_e32 v131, 31, v119
	v_or_b32_e32 v131, s29, v131
	v_xor_b32_e32 v119, v119, v131
	v_cndmask_b32_e64 v119, 0, v119, s[36:37]
	s_sub_i32 s0, s30, 1408
	v_cmp_gt_i32_e64 s[38:39], s0, v178
	v_ashrrev_i32_e32 v130, 31, v120
	v_or_b32_e32 v130, s29, v130
	v_xor_b32_e32 v120, v120, v130
	v_cndmask_b32_e64 v120, 0, v120, s[38:39]
	s_sub_i32 s1, s30, 1472
	v_cmp_gt_i32_e64 s[40:41], s1, v178
	v_ashrrev_i32_e32 v131, 31, v121
	v_or_b32_e32 v131, s29, v131
	v_xor_b32_e32 v121, v121, v131
	v_cndmask_b32_e64 v121, 0, v121, s[40:41]
	s_cmp_lt_u32 s27, 4
	s_cbranch_scc1 .Lsel_cdone
	s_waitcnt lgkmcnt(4)
	s_sub_i32 s0, s28, 1536
	v_cmp_gt_i32_e64 s[34:35], s0, v178
	v_ashrrev_i32_e32 v130, 31, v90
	v_or_b32_e32 v130, s29, v130
	v_xor_b32_e32 v90, v90, v130
	v_cndmask_b32_e64 v90, 0, v90, s[34:35]
	s_sub_i32 s1, s28, 1600
	v_cmp_gt_i32_e64 s[36:37], s1, v178
	v_ashrrev_i32_e32 v131, 31, v91
	v_or_b32_e32 v131, s29, v131
	v_xor_b32_e32 v91, v91, v131
	v_cndmask_b32_e64 v91, 0, v91, s[36:37]
	s_sub_i32 s0, s28, 1664
	v_cmp_gt_i32_e64 s[38:39], s0, v178
	v_ashrrev_i32_e32 v130, 31, v92
	v_or_b32_e32 v130, s29, v130
	v_xor_b32_e32 v92, v92, v130
	v_cndmask_b32_e64 v92, 0, v92, s[38:39]
	s_sub_i32 s1, s28, 1728
	v_cmp_gt_i32_e64 s[40:41], s1, v178
	v_ashrrev_i32_e32 v131, 31, v93
	v_or_b32_e32 v131, s29, v131
	v_xor_b32_e32 v93, v93, v131
	v_cndmask_b32_e64 v93, 0, v93, s[40:41]
	s_sub_i32 s0, s28, 1792
	v_cmp_gt_i32_e64 s[34:35], s0, v178
	v_ashrrev_i32_e32 v130, 31, v94
	v_or_b32_e32 v130, s29, v130
	v_xor_b32_e32 v94, v94, v130
	v_cndmask_b32_e64 v94, 0, v94, s[34:35]
	s_sub_i32 s1, s28, 1856
	v_cmp_gt_i32_e64 s[36:37], s1, v178
	v_ashrrev_i32_e32 v131, 31, v95
	v_or_b32_e32 v131, s29, v131
	v_xor_b32_e32 v95, v95, v131
	v_cndmask_b32_e64 v95, 0, v95, s[36:37]
	s_sub_i32 s0, s28, 1920
	v_cmp_gt_i32_e64 s[38:39], s0, v178
	v_ashrrev_i32_e32 v130, 31, v96
	v_or_b32_e32 v130, s29, v130
	v_xor_b32_e32 v96, v96, v130
	v_cndmask_b32_e64 v96, 0, v96, s[38:39]
	s_sub_i32 s1, s28, 1984
	v_cmp_gt_i32_e64 s[40:41], s1, v178
	v_ashrrev_i32_e32 v131, 31, v97
	v_or_b32_e32 v131, s29, v131
	v_xor_b32_e32 v97, v97, v131
	v_cndmask_b32_e64 v97, 0, v97, s[40:41]
	s_waitcnt lgkmcnt(0)
	s_sub_i32 s0, s30, 1536
	v_cmp_gt_i32_e64 s[34:35], s0, v178
	v_ashrrev_i32_e32 v130, 31, v122
	v_or_b32_e32 v130, s29, v130
	v_xor_b32_e32 v122, v122, v130
	v_cndmask_b32_e64 v122, 0, v122, s[34:35]
	s_sub_i32 s1, s30, 1600
	v_cmp_gt_i32_e64 s[36:37], s1, v178
	v_ashrrev_i32_e32 v131, 31, v123
	v_or_b32_e32 v131, s29, v131
	v_xor_b32_e32 v123, v123, v131
	v_cndmask_b32_e64 v123, 0, v123, s[36:37]
	s_sub_i32 s0, s30, 1664
	v_cmp_gt_i32_e64 s[38:39], s0, v178
	v_ashrrev_i32_e32 v130, 31, v124
	v_or_b32_e32 v130, s29, v130
	v_xor_b32_e32 v124, v124, v130
	v_cndmask_b32_e64 v124, 0, v124, s[38:39]
	s_sub_i32 s1, s30, 1728
	v_cmp_gt_i32_e64 s[40:41], s1, v178
	v_ashrrev_i32_e32 v131, 31, v125
	v_or_b32_e32 v131, s29, v131
	v_xor_b32_e32 v125, v125, v131
	v_cndmask_b32_e64 v125, 0, v125, s[40:41]
	s_sub_i32 s0, s30, 1792
	v_cmp_gt_i32_e64 s[34:35], s0, v178
	v_ashrrev_i32_e32 v130, 31, v126
	v_or_b32_e32 v130, s29, v130
	v_xor_b32_e32 v126, v126, v130
	v_cndmask_b32_e64 v126, 0, v126, s[34:35]
	s_sub_i32 s1, s30, 1856
	v_cmp_gt_i32_e64 s[36:37], s1, v178
	v_ashrrev_i32_e32 v131, 31, v127
	v_or_b32_e32 v131, s29, v131
	v_xor_b32_e32 v127, v127, v131
	v_cndmask_b32_e64 v127, 0, v127, s[36:37]
	s_sub_i32 s0, s30, 1920
	v_cmp_gt_i32_e64 s[38:39], s0, v178
	v_ashrrev_i32_e32 v130, 31, v128
	v_or_b32_e32 v130, s29, v130
	v_xor_b32_e32 v128, v128, v130
	v_cndmask_b32_e64 v128, 0, v128, s[38:39]
	s_sub_i32 s1, s30, 1984
	v_cmp_gt_i32_e64 s[40:41], s1, v178
	v_ashrrev_i32_e32 v131, 31, v129
	v_or_b32_e32 v131, s29, v131
	v_xor_b32_e32 v129, v129, v131
	v_cndmask_b32_e64 v129, 0, v129, s[40:41]
.Lsel_cdone:
	s_waitcnt lgkmcnt(0)
	s_mov_b32 s6, 0
	s_mov_b32 s7, 0
	s_cmpk_gt_i32 s10, 0xfe
	s_cbranch_scc0 .Lsel_final
	s_mov_b32 s24, 31
	s_mov_b32 s8, 0
	s_mov_b32 s9, 0
.Lsel_step:
	s_lshl_b32 s0, 1, s24
	s_or_b32 s12, s6, s0
	s_or_b32 s13, s7, s0
	s_mov_b32 s25, 0
	s_mov_b32 s26, 0
	v_cmp_le_u32_e64 s[34:35], s12, v66
	v_cmp_le_u32_e64 s[42:43], s13, v98
	v_cmp_le_u32_e64 s[36:37], s12, v67
	v_cmp_le_u32_e64 s[44:45], s13, v99
	v_cmp_le_u32_e64 s[38:39], s12, v68
	v_cmp_le_u32_e64 s[46:47], s13, v100
	v_cmp_le_u32_e64 s[40:41], s12, v69
	v_cmp_le_u32_e64 s[48:49], s13, v101
	s_bcnt1_i32_b64 s0, s[34:35]
	v_cmp_le_u32_e64 s[34:35], s12, v70
	s_add_i32 s25, s25, s0
	s_bcnt1_i32_b64 s1, s[42:43]
	v_cmp_le_u32_e64 s[42:43], s13, v102
	s_add_i32 s26, s26, s1
	s_bcnt1_i32_b64 s0, s[36:37]
	v_cmp_le_u32_e64 s[36:37], s12, v71
	s_add_i32 s25, s25, s0
	s_bcnt1_i32_b64 s1, s[44:45]
	v_cmp_le_u32_e64 s[44:45], s13, v103
	s_add_i32 s26, s26, s1
	s_bcnt1_i32_b64 s0, s[38:39]
	v_cmp_le_u32_e64 s[38:39], s12, v72
	s_add_i32 s25, s25, s0
	s_bcnt1_i32_b64 s1, s[46:47]
	v_cmp_le_u32_e64 s[46:47], s13, v104
	s_add_i32 s26, s26, s1
	s_bcnt1_i32_b64 s0, s[40:41]
	v_cmp_le_u32_e64 s[40:41], s12, v73
	s_add_i32 s25, s25, s0
	s_bcnt1_i32_b64 s1, s[48:49]
	v_cmp_le_u32_e64 s[48:49], s13, v105
	s_add_i32 s26, s26, s1
	s_bcnt1_i32_b64 s0, s[34:35]
	s_bcnt1_i32_b64 s1, s[42:43]
	s_add_i32 s25, s25, s0
	s_add_i32 s26, s26, s1
	s_bcnt1_i32_b64 s0, s[36:37]
	s_bcnt1_i32_b64 s1, s[44:45]
	s_add_i32 s25, s25, s0
	s_add_i32 s26, s26, s1
	s_bcnt1_i32_b64 s0, s[38:39]
	s_bcnt1_i32_b64 s1, s[46:47]
	s_add_i32 s25, s25, s0
	s_add_i32 s26, s26, s1
	s_bcnt1_i32_b64 s0, s[40:41]
	s_bcnt1_i32_b64 s1, s[48:49]
	s_add_i32 s25, s25, s0
	s_add_i32 s26, s26, s1
	s_cmp_lt_u32 s27, 2
	s_cbranch_scc1 .Lsel_cnt
	v_cmp_le_u32_e64 s[34:35], s12, v74
	v_cmp_le_u32_e64 s[42:43], s13, v106
	v_cmp_le_u32_e64 s[36:37], s12, v75
	v_cmp_le_u32_e64 s[44:45], s13, v107
	v_cmp_le_u32_e64 s[38:39], s12, v76
	v_cmp_le_u32_e64 s[46:47], s13, v108
	v_cmp_le_u32_e64 s[40:41], s12, v77
	v_cmp_le_u32_e64 s[48:49], s13, v109
	s_bcnt1_i32_b64 s0, s[34:35]
	v_cmp_le_u32_e64 s[34:35], s12, v78
	s_add_i32 s25, s25, s0
	s_bcnt1_i32_b64 s1, s[42:43]
	v_cmp_le_u32_e64 s[42:43], s13, v110
	s_add_i32 s26, s26, s1
	s_bcnt1_i32_b64 s0, s[36:37]
	v_cmp_le_u32_e64 s[36:37], s12, v79
	s_add_i32 s25, s25, s0
	s_bcnt1_i32_b64 s1, s[44:45]
	v_cmp_le_u32_e64 s[44:45], s13, v111
	s_add_i32 s26, s26, s1
	s_bcnt1_i32_b64 s0, s[38:39]
	v_cmp_le_u32_e64 s[38:39], s12, v80
	s_add_i32 s25, s25, s0
	s_bcnt1_i32_b64 s1, s[46:47]
	v_cmp_le_u32_e64 s[46:47], s13, v112
	s_add_i32 s26, s26, s1
	s_bcnt1_i32_b64 s0, s[40:41]
	v_cmp_le_u32_e64 s[40:41], s12, v81
	s_add_i32 s25, s25, s0
	s_bcnt1_i32_b64 s1, s[48:49]
	v_cmp_le_u32_e64 s[48:49], s13, v113
	s_add_i32 s26, s26, s1
	s_bcnt1_i32_b64 s0, s[34:35]
	s_bcnt1_i32_b64 s1, s[42:43]
	s_add_i32 s25, s25, s0
	s_add_i32 s26, s26, s1
	s_bcnt1_i32_b64 s0, s[36:37]
	s_bcnt1_i32_b64 s1, s[44:45]
	s_add_i32 s25, s25, s0
	s_add_i32 s26, s26, s1
	s_bcnt1_i32_b64 s0, s[38:39]
	s_bcnt1_i32_b64 s1, s[46:47]
	s_add_i32 s25, s25, s0
	s_add_i32 s26, s26, s1
	s_bcnt1_i32_b64 s0, s[40:41]
	s_bcnt1_i32_b64 s1, s[48:49]
	s_add_i32 s25, s25, s0
	s_add_i32 s26, s26, s1
	s_cmp_lt_u32 s27, 3
	s_cbranch_scc1 .Lsel_cnt
	v_cmp_le_u32_e64 s[34:35], s12, v82
	v_cmp_le_u32_e64 s[42:43], s13, v114
	v_cmp_le_u32_e64 s[36:37], s12, v83
	v_cmp_le_u32_e64 s[44:45], s13, v115
	v_cmp_le_u32_e64 s[38:39], s12, v84
	v_cmp_le_u32_e64 s[46:47], s13, v116
	v_cmp_le_u32_e64 s[40:41], s12, v85
	v_cmp_le_u32_e64 s[48:49], s13, v117
	s_bcnt1_i32_b64 s0, s[34:35]
	v_cmp_le_u32_e64 s[34:35], s12, v86
	s_add_i32 s25, s25, s0
	s_bcnt1_i32_b64 s1, s[42:43]
	v_cmp_le_u32_e64 s[42:43], s13, v118
	s_add_i32 s26, s26, s1
	s_bcnt1_i32_b64 s0, s[36:37]
	v_cmp_le_u32_e64 s[36:37], s12, v87
	s_add_i32 s25, s25, s0
	s_bcnt1_i32_b64 s1, s[44:45]
	v_cmp_le_u32_e64 s[44:45], s13, v119
	s_add_i32 s26, s26, s1
	s_bcnt1_i32_b64 s0, s[38:39]
	v_cmp_le_u32_e64 s[38:39], s12, v88
	s_add_i32 s25, s25, s0
	s_bcnt1_i32_b64 s1, s[46:47]
	v_cmp_le_u32_e64 s[46:47], s13, v120
	s_add_i32 s26, s26, s1
	s_bcnt1_i32_b64 s0, s[40:41]
	v_cmp_le_u32_e64 s[40:41], s12, v89
	s_add_i32 s25, s25, s0
	s_bcnt1_i32_b64 s1, s[48:49]
	v_cmp_le_u32_e64 s[48:49], s13, v121
	s_add_i32 s26, s26, s1
	s_bcnt1_i32_b64 s0, s[34:35]
	s_bcnt1_i32_b64 s1, s[42:43]
	s_add_i32 s25, s25, s0
	s_add_i32 s26, s26, s1
	s_bcnt1_i32_b64 s0, s[36:37]
	s_bcnt1_i32_b64 s1, s[44:45]
	s_add_i32 s25, s25, s0
	s_add_i32 s26, s26, s1
	s_bcnt1_i32_b64 s0, s[38:39]
	s_bcnt1_i32_b64 s1, s[46:47]
	s_add_i32 s25, s25, s0
	s_add_i32 s26, s26, s1
	s_bcnt1_i32_b64 s0, s[40:41]
	s_bcnt1_i32_b64 s1, s[48:49]
	s_add_i32 s25, s25, s0
	s_add_i32 s26, s26, s1
	s_cmp_lt_u32 s27, 4
	s_cbranch_scc1 .Lsel_cnt
	v_cmp_le_u32_e64 s[34:35], s12, v90
	v_cmp_le_u32_e64 s[42:43], s13, v122
	v_cmp_le_u32_e64 s[36:37], s12, v91
	v_cmp_le_u32_e64 s[44:45], s13, v123
	v_cmp_le_u32_e64 s[38:39], s12, v92
	v_cmp_le_u32_e64 s[46:47], s13, v124
	v_cmp_le_u32_e64 s[40:41], s12, v93
	v_cmp_le_u32_e64 s[48:49], s13, v125
	s_bcnt1_i32_b64 s0, s[34:35]
	v_cmp_le_u32_e64 s[34:35], s12, v94
	s_add_i32 s25, s25, s0
	s_bcnt1_i32_b64 s1, s[42:43]
	v_cmp_le_u32_e64 s[42:43], s13, v126
	s_add_i32 s26, s26, s1
	s_bcnt1_i32_b64 s0, s[36:37]
	v_cmp_le_u32_e64 s[36:37], s12, v95
	s_add_i32 s25, s25, s0
	s_bcnt1_i32_b64 s1, s[44:45]
	v_cmp_le_u32_e64 s[44:45], s13, v127
	s_add_i32 s26, s26, s1
	s_bcnt1_i32_b64 s0, s[38:39]
	v_cmp_le_u32_e64 s[38:39], s12, v96
	s_add_i32 s25, s25, s0
	s_bcnt1_i32_b64 s1, s[46:47]
	v_cmp_le_u32_e64 s[46:47], s13, v128
	s_add_i32 s26, s26, s1
	s_bcnt1_i32_b64 s0, s[40:41]
	v_cmp_le_u32_e64 s[40:41], s12, v97
	s_add_i32 s25, s25, s0
	s_bcnt1_i32_b64 s1, s[48:49]
	v_cmp_le_u32_e64 s[48:49], s13, v129
	s_add_i32 s26, s26, s1
	s_bcnt1_i32_b64 s0, s[34:35]
	s_bcnt1_i32_b64 s1, s[42:43]
	s_add_i32 s25, s25, s0
	s_add_i32 s26, s26, s1
	s_bcnt1_i32_b64 s0, s[36:37]
	s_bcnt1_i32_b64 s1, s[44:45]
	s_add_i32 s25, s25, s0
	s_add_i32 s26, s26, s1
	s_bcnt1_i32_b64 s0, s[38:39]
	s_bcnt1_i32_b64 s1, s[46:47]
	s_add_i32 s25, s25, s0
	s_add_i32 s26, s26, s1
	s_bcnt1_i32_b64 s0, s[40:41]
	s_bcnt1_i32_b64 s1, s[48:49]
	s_add_i32 s25, s25, s0
	s_add_i32 s26, s26, s1
.Lsel_cnt:
	s_cmpk_gt_u32 s25, 0xff
	s_cselect_b32 s6, s12, s6
	s_cmpk_gt_u32 s26, 0xff
	s_cselect_b32 s7, s13, s7
	s_cmpk_eq_u32 s25, 0x100
	s_cselect_b32 s8, 1, s8
	s_cmpk_eq_u32 s26, 0x100
	s_cselect_b32 s9, 1, s9
	s_and_b32 s0, s8, s9
	s_cmp_lg_u32 s0, 0
	s_cbranch_scc1 .Lsel_final
	s_add_i32 s24, s24, -1
	s_cmp_ge_i32 s24, 0
	s_cbranch_scc1 .Lsel_step
.Lsel_final:
	s_max_u32 s6, s6, 1
	s_max_u32 s7, s7, 1
	v_mov_b32_e32 v132, 0
	v_mov_b32_e32 v133, 0
	v_mov_b32_e32 v134, 0
	v_mov_b32_e32 v135, 0
	v_cmp_le_u32_e64 s[34:35], s6, v66
	v_cmp_le_u32_e64 s[42:43], s7, v98
	v_cmp_le_u32_e64 s[36:37], s6, v67
	v_cmp_le_u32_e64 s[44:45], s7, v99
	v_writelane_b32 v132, s34, 0
	v_writelane_b32 v133, s35, 0
	v_writelane_b32 v134, s42, 0
	v_writelane_b32 v135, s43, 0
	v_writelane_b32 v132, s36, 1
	v_writelane_b32 v133, s37, 1
	v_writelane_b32 v134, s44, 1
	v_writelane_b32 v135, s45, 1
	v_cmp_le_u32_e64 s[34:35], s6, v68
	v_cmp_le_u32_e64 s[42:43], s7, v100
	v_cmp_le_u32_e64 s[36:37], s6, v69
	v_cmp_le_u32_e64 s[44:45], s7, v101
	v_writelane_b32 v132, s34, 2
	v_writelane_b32 v133, s35, 2
	v_writelane_b32 v134, s42, 2
	v_writelane_b32 v135, s43, 2
	v_writelane_b32 v132, s36, 3
	v_writelane_b32 v133, s37, 3
	v_writelane_b32 v134, s44, 3
	v_writelane_b32 v135, s45, 3
	v_cmp_le_u32_e64 s[34:35], s6, v70
	v_cmp_le_u32_e64 s[42:43], s7, v102
	v_cmp_le_u32_e64 s[36:37], s6, v71
	v_cmp_le_u32_e64 s[44:45], s7, v103
	v_writelane_b32 v132, s34, 4
	v_writelane_b32 v133, s35, 4
	v_writelane_b32 v134, s42, 4
	v_writelane_b32 v135, s43, 4
	v_writelane_b32 v132, s36, 5
	v_writelane_b32 v133, s37, 5
	v_writelane_b32 v134, s44, 5
	v_writelane_b32 v135, s45, 5
	v_cmp_le_u32_e64 s[34:35], s6, v72
	v_cmp_le_u32_e64 s[42:43], s7, v104
	v_cmp_le_u32_e64 s[36:37], s6, v73
	v_cmp_le_u32_e64 s[44:45], s7, v105
	v_writelane_b32 v132, s34, 6
	v_writelane_b32 v133, s35, 6
	v_writelane_b32 v134, s42, 6
	v_writelane_b32 v135, s43, 6
	v_writelane_b32 v132, s36, 7
	v_writelane_b32 v133, s37, 7
	v_writelane_b32 v134, s44, 7
	v_writelane_b32 v135, s45, 7
	s_cmp_lt_u32 s27, 2
	s_cbranch_scc1 .Lsel_store
	v_cmp_le_u32_e64 s[34:35], s6, v74
	v_cmp_le_u32_e64 s[42:43], s7, v106
	v_cmp_le_u32_e64 s[36:37], s6, v75
	v_cmp_le_u32_e64 s[44:45], s7, v107
	v_writelane_b32 v132, s34, 8
	v_writelane_b32 v133, s35, 8
	v_writelane_b32 v134, s42, 8
	v_writelane_b32 v135, s43, 8
	v_writelane_b32 v132, s36, 9
	v_writelane_b32 v133, s37, 9
	v_writelane_b32 v134, s44, 9
	v_writelane_b32 v135, s45, 9
	v_cmp_le_u32_e64 s[34:35], s6, v76
	v_cmp_le_u32_e64 s[42:43], s7, v108
	v_cmp_le_u32_e64 s[36:37], s6, v77
	v_cmp_le_u32_e64 s[44:45], s7, v109
	v_writelane_b32 v132, s34, 10
	v_writelane_b32 v133, s35, 10
	v_writelane_b32 v134, s42, 10
	v_writelane_b32 v135, s43, 10
	v_writelane_b32 v132, s36, 11
	v_writelane_b32 v133, s37, 11
	v_writelane_b32 v134, s44, 11
	v_writelane_b32 v135, s45, 11
	v_cmp_le_u32_e64 s[34:35], s6, v78
	v_cmp_le_u32_e64 s[42:43], s7, v110
	v_cmp_le_u32_e64 s[36:37], s6, v79
	v_cmp_le_u32_e64 s[44:45], s7, v111
	v_writelane_b32 v132, s34, 12
	v_writelane_b32 v133, s35, 12
	v_writelane_b32 v134, s42, 12
	v_writelane_b32 v135, s43, 12
	v_writelane_b32 v132, s36, 13
	v_writelane_b32 v133, s37, 13
	v_writelane_b32 v134, s44, 13
	v_writelane_b32 v135, s45, 13
	v_cmp_le_u32_e64 s[34:35], s6, v80
	v_cmp_le_u32_e64 s[42:43], s7, v112
	v_cmp_le_u32_e64 s[36:37], s6, v81
	v_cmp_le_u32_e64 s[44:45], s7, v113
	v_writelane_b32 v132, s34, 14
	v_writelane_b32 v133, s35, 14
	v_writelane_b32 v134, s42, 14
	v_writelane_b32 v135, s43, 14
	v_writelane_b32 v132, s36, 15
	v_writelane_b32 v133, s37, 15
	v_writelane_b32 v134, s44, 15
	v_writelane_b32 v135, s45, 15
	s_cmp_lt_u32 s27, 3
	s_cbranch_scc1 .Lsel_store
	v_cmp_le_u32_e64 s[34:35], s6, v82
	v_cmp_le_u32_e64 s[42:43], s7, v114
	v_cmp_le_u32_e64 s[36:37], s6, v83
	v_cmp_le_u32_e64 s[44:45], s7, v115
	v_writelane_b32 v132, s34, 16
	v_writelane_b32 v133, s35, 16
	v_writelane_b32 v134, s42, 16
	v_writelane_b32 v135, s43, 16
	v_writelane_b32 v132, s36, 17
	v_writelane_b32 v133, s37, 17
	v_writelane_b32 v134, s44, 17
	v_writelane_b32 v135, s45, 17
	v_cmp_le_u32_e64 s[34:35], s6, v84
	v_cmp_le_u32_e64 s[42:43], s7, v116
	v_cmp_le_u32_e64 s[36:37], s6, v85
	v_cmp_le_u32_e64 s[44:45], s7, v117
	v_writelane_b32 v132, s34, 18
	v_writelane_b32 v133, s35, 18
	v_writelane_b32 v134, s42, 18
	v_writelane_b32 v135, s43, 18
	v_writelane_b32 v132, s36, 19
	v_writelane_b32 v133, s37, 19
	v_writelane_b32 v134, s44, 19
	v_writelane_b32 v135, s45, 19
	v_cmp_le_u32_e64 s[34:35], s6, v86
	v_cmp_le_u32_e64 s[42:43], s7, v118
	v_cmp_le_u32_e64 s[36:37], s6, v87
	v_cmp_le_u32_e64 s[44:45], s7, v119
	v_writelane_b32 v132, s34, 20
	v_writelane_b32 v133, s35, 20
	v_writelane_b32 v134, s42, 20
	v_writelane_b32 v135, s43, 20
	v_writelane_b32 v132, s36, 21
	v_writelane_b32 v133, s37, 21
	v_writelane_b32 v134, s44, 21
	v_writelane_b32 v135, s45, 21
	v_cmp_le_u32_e64 s[34:35], s6, v88
	v_cmp_le_u32_e64 s[42:43], s7, v120
	v_cmp_le_u32_e64 s[36:37], s6, v89
	v_cmp_le_u32_e64 s[44:45], s7, v121
	v_writelane_b32 v132, s34, 22
	v_writelane_b32 v133, s35, 22
	v_writelane_b32 v134, s42, 22
	v_writelane_b32 v135, s43, 22
	v_writelane_b32 v132, s36, 23
	v_writelane_b32 v133, s37, 23
	v_writelane_b32 v134, s44, 23
	v_writelane_b32 v135, s45, 23
	s_cmp_lt_u32 s27, 4
	s_cbranch_scc1 .Lsel_store
	v_cmp_le_u32_e64 s[34:35], s6, v90
	v_cmp_le_u32_e64 s[42:43], s7, v122
	v_cmp_le_u32_e64 s[36:37], s6, v91
	v_cmp_le_u32_e64 s[44:45], s7, v123
	v_writelane_b32 v132, s34, 24
	v_writelane_b32 v133, s35, 24
	v_writelane_b32 v134, s42, 24
	v_writelane_b32 v135, s43, 24
	v_writelane_b32 v132, s36, 25
	v_writelane_b32 v133, s37, 25
	v_writelane_b32 v134, s44, 25
	v_writelane_b32 v135, s45, 25
	v_cmp_le_u32_e64 s[34:35], s6, v92
	v_cmp_le_u32_e64 s[42:43], s7, v124
	v_cmp_le_u32_e64 s[36:37], s6, v93
	v_cmp_le_u32_e64 s[44:45], s7, v125
	v_writelane_b32 v132, s34, 26
	v_writelane_b32 v133, s35, 26
	v_writelane_b32 v134, s42, 26
	v_writelane_b32 v135, s43, 26
	v_writelane_b32 v132, s36, 27
	v_writelane_b32 v133, s37, 27
	v_writelane_b32 v134, s44, 27
	v_writelane_b32 v135, s45, 27
	v_cmp_le_u32_e64 s[34:35], s6, v94
	v_cmp_le_u32_e64 s[42:43], s7, v126
	v_cmp_le_u32_e64 s[36:37], s6, v95
	v_cmp_le_u32_e64 s[44:45], s7, v127
	v_writelane_b32 v132, s34, 28
	v_writelane_b32 v133, s35, 28
	v_writelane_b32 v134, s42, 28
	v_writelane_b32 v135, s43, 28
	v_writelane_b32 v132, s36, 29
	v_writelane_b32 v133, s37, 29
	v_writelane_b32 v134, s44, 29
	v_writelane_b32 v135, s45, 29
	v_cmp_le_u32_e64 s[34:35], s6, v96
	v_cmp_le_u32_e64 s[42:43], s7, v128
	v_cmp_le_u32_e64 s[36:37], s6, v97
	v_cmp_le_u32_e64 s[44:45], s7, v129
	v_writelane_b32 v132, s34, 30
	v_writelane_b32 v133, s35, 30
	v_writelane_b32 v134, s42, 30
	v_writelane_b32 v135, s43, 30
	v_writelane_b32 v132, s36, 31
	v_writelane_b32 v133, s37, 31
	v_writelane_b32 v134, s44, 31
	v_writelane_b32 v135, s45, 31
.Lsel_store:
	s_add_i32 s0, s10, s33
	s_mov_b32 s1, 0
	s_lshl_b64 s[0:1], s[0:1], 8
	s_nop 1
	v_lshl_add_u64 v[136:137], v[236:237], 0, s[0:1]
	s_mov_b32 exec_lo, -1
	s_mov_b32 exec_hi, 0
	global_store_dwordx2 v[136:137], v[132:133], off
	global_store_dwordx2 v[136:137], v[134:135], off offset:256
	s_mov_b64 exec, -1
	s_mov_b64 s[30:31], -1
	s_branch .LBB0_104
